# v25 + prologue convert_tiles job lookup scans only the 3 layer-0 candidates instead of all 19 jobs (dependent scalar loads)
# speedup vs baseline: 1.0278x; 1.0047x over previous
.LBB0_813:
	v_mov_b32_e32 v13, v206
	s_load_dword s4, s[0:1], 0x614
	v_ashrrev_i32_e32 v0, 7, v13
	v_and_b32_e32 v26, -2, v0
	v_lshl_add_u32 v8, s48, 2, v26
	s_waitcnt lgkmcnt(0)
	v_mov_b64_e32 v[2:3], 0
	v_cmp_gt_i32_e64 s[40:41], s4, v8
	v_readlane_b32 s4, v253, 59
	v_readlane_b32 s5, v253, 60
	s_andn2_b64 vcc, exec, s[4:5]
	v_cndmask_b32_e64 v0, 0, v8, s[40:41]
	v_cndmask_b32_e64 v3, 0, 1, s[4:5]
	v_readlane_b32 s4, v254, 23
	v_readlane_b32 s5, v254, 24
	v_cmp_ne_u32_e64 s[46:47], 1, v3
	s_nop 0
	v_cndmask_b32_e64 v3, 0, 1, s[4:5]
	v_cmp_ne_u32_e64 s[44:45], 1, v3
	s_cbranch_vccnz .LBB0_821
	s_and_b64 vcc, exec, s[44:45]
	s_mov_b32 s22, 1
	s_cbranch_vccnz .LBB0_818
	v_mov_b32_e32 v3, v0
	s_mov_b32 s20, 2
	s_mov_b32 s21, 1
	v_bfrev_b32_e32 v2, 1
	s_mov_b32 s22, 2
	v_bfrev_b32_e32 v4, 1
.LBB0_816:
	s_mul_i32 s26, s21, 56
	s_mul_hi_u32 s23, s21, 56
	s_add_u32 s26, s0, s26
	s_addc_u32 s27, s1, s23
	s_mul_i32 s28, s20, 56
	s_mul_hi_u32 s23, s20, 56
	s_add_u32 s28, s0, s28
	s_addc_u32 s29, s1, s23
	s_load_dword s23, s[26:27], 0x1cc
	s_nop 0
	s_load_dword s26, s[28:29], 0x1cc
	v_mov_b32_e32 v5, s20
	s_add_i32 s20, s20, 2
	s_add_i32 s22, s22, -2
	s_waitcnt lgkmcnt(0)
	v_cmp_gt_i32_e32 vcc, s23, v0
	v_cmp_gt_i32_e64 s[42:43], s26, v3
	s_nop 1
	v_cndmask_b32_e64 v4, v5, v4, s[42:43]
	v_mov_b32_e32 v5, s21
	s_add_i32 s21, s21, 2
	v_cndmask_b32_e32 v2, v5, v2, vcc
	s_cmp_lg_u32 s22, 0
	s_cbranch_scc1 .LBB0_816
	v_max_i32_e32 v2, v2, v4
	s_brev_b32 s4, 1
	v_cmp_ne_u32_e32 vcc, s4, v2
	v_readlane_b32 s20, v254, 27
	s_mov_b32 s22, 3
	v_cndmask_b32_e32 v2, 0, v2, vcc
	v_readlane_b32 s21, v254, 28
	s_mov_b64 vcc, exec
	s_cbranch_vccnz .LBB0_819
	s_branch .LBB0_821

.LBB0_820:
	s_load_dword s23, s[20:21], 0x0
	v_mov_b32_e32 v3, s22
	s_add_i32 s22, s22, 1
	s_add_u32 s20, s20, 56
	s_addc_u32 s21, s21, 0
	s_waitcnt lgkmcnt(0)
	v_cmp_gt_i32_e32 vcc, s23, v0
	s_cmp_eq_u32 s22, 4
	s_nop 0
	v_cndmask_b32_e32 v2, v3, v2, vcc
	s_cbranch_scc0 .LBB0_820

.LBB0_829:
	s_or_b64 exec, exec, s[22:23]
	s_and_saveexec_b64 s[22:23], s[20:21]
	v_lshlrev_b32_e32 v2, 5, v0
	s_movk_i32 s4, 0x7f
	v_bfe_i32 v0, v0, 1, 1
	v_bfi_b32 v2, s4, v4, v2
	v_and_b32_e32 v0, 0xb00, v0
	v_add_u32_e32 v20, v2, v0
	s_or_b64 s[26:27], s[26:27], exec
	s_or_b64 exec, exec, s[22:23]
	global_load_dwordx3 v[10:12], v[6:7], off offset:424
	global_load_dwordx4 v[2:5], v[6:7], off offset:408
	global_load_dword v23, v[6:7], off offset:440
	s_load_dword s4, s[0:1], 0x614
	v_or_b32_e32 v0, 1, v8
	s_and_b64 vcc, exec, s[46:47]
	v_mov_b64_e32 v[6:7], 0
	s_waitcnt lgkmcnt(0)
	v_cmp_gt_i32_e64 s[42:43], s4, v0
	s_nop 1
	v_cndmask_b32_e64 v0, 0, v0, s[42:43]
	s_cbranch_vccnz .LBB0_839
	s_and_b64 vcc, exec, s[44:45]
	s_mov_b32 s22, 1
	s_cbranch_vccnz .LBB0_836
	v_mov_b32_e32 v7, v0
	s_mov_b32 s20, 2
	s_mov_b32 s21, 1
	v_bfrev_b32_e32 v6, 1
	s_mov_b32 s22, 2
	v_bfrev_b32_e32 v8, 1
.LBB0_834:
	s_mul_i32 s28, s21, 56
	s_mul_hi_u32 s23, s21, 56
	s_add_u32 s28, s0, s28
	s_addc_u32 s29, s1, s23
	s_mul_i32 s30, s20, 56
	s_mul_hi_u32 s23, s20, 56
	s_add_u32 s30, s0, s30
	s_addc_u32 s31, s1, s23
	s_load_dword s23, s[28:29], 0x1cc
	s_nop 0
	s_load_dword s28, s[30:31], 0x1cc
	v_mov_b32_e32 v9, s20
	s_add_i32 s20, s20, 2
	s_add_i32 s22, s22, -2
	s_waitcnt lgkmcnt(0)
	v_cmp_gt_i32_e32 vcc, s23, v0
	v_cmp_gt_i32_e64 s[44:45], s28, v7
	s_nop 1
	v_cndmask_b32_e64 v8, v9, v8, s[44:45]
	v_mov_b32_e32 v9, s21
	s_add_i32 s21, s21, 2
	v_cndmask_b32_e32 v6, v9, v6, vcc
	s_cmp_lg_u32 s22, 0
	s_cbranch_scc1 .LBB0_834
	v_max_i32_e32 v6, v6, v8
	s_brev_b32 s4, 1
	v_cmp_ne_u32_e32 vcc, s4, v6
	v_readlane_b32 s20, v254, 27
	s_mov_b32 s22, 3
	v_cndmask_b32_e32 v6, 0, v6, vcc
	v_readlane_b32 s21, v254, 28
	s_mov_b64 vcc, exec
	s_cbranch_vccnz .LBB0_837
	s_branch .LBB0_839

.LBB0_838:
	s_load_dword s23, s[20:21], 0x0
	v_mov_b32_e32 v7, s22
	s_add_i32 s22, s22, 1
	s_add_u32 s20, s20, 56
	s_addc_u32 s21, s21, 0
	s_waitcnt lgkmcnt(0)
	v_cmp_gt_i32_e32 vcc, s23, v0
	s_cmp_eq_u32 s22, 4
	s_nop 0
	v_cndmask_b32_e32 v6, v7, v6, vcc
	s_cbranch_scc0 .LBB0_838
